# v54 + one static s_setprio 1 for waves 4-7 at each attention unit entry
# baseline (speedup 1.0000x reference)
; __device__ void mixer_phase(const Params& P, int l, unsigned char* smem) {
;     ...
;     for (;;) {
;         __syncthreads();
;         if (tid0 == 0) slot[0] = atomicAdd(ctr, 1u);
;         __syncthreads();
;         const unsigned u = slot[0];
.LBB0_141:
	s_barrier
	v_readfirstlane_b32 s0, v154
	s_nop 3
	s_cmp_lt_u32 s0, 0x100
	s_cbranch_scc1 .Latt_noprio
	s_setprio 1
.Latt_noprio:
	s_and_saveexec_b64 s[0:1], s[4:5]
	s_cbranch_execz .LBB0_145
	s_mov_b64 s[8:9], exec
	v_mbcnt_lo_u32_b32 v0, s8, 0
	v_mbcnt_hi_u32_b32 v0, s9, v0
	v_cmp_eq_u32_e32 vcc, 0, v0
	s_and_saveexec_b64 s[6:7], vcc
	s_cbranch_execz .LBB0_144
	s_bcnt1_i32_b64 s2, s[8:9]
	v_mov_b32_e32 v1, s2
	global_atomic_add v1, v113, v1, s[36:37] sc0
